# stack of all small changes plus P3 K-loop touch of the residual x tile (forward order)
# baseline (speedup 1.0000x reference)
.Lprio_skip2:
.LBB0_495:
	v_add_u32_e32 v147, s53, v145
	ds_read_b128 v[148:151], v147
	ds_read_b128 v[152:155], v147 offset:1024
	ds_read_b128 v[156:159], v147 offset:2048
	ds_read_b128 v[160:163], v147 offset:3072
	v_add_u32_e32 v147, s54, v145
	s_add_u32 s34, s16, s30
	ds_read_b128 v[164:167], v147
	ds_read_b128 v[172:175], v147 offset:1024
	ds_read_b128 v[176:179], v147 offset:2048
	ds_read_b128 v[180:183], v147 offset:3072
	s_addc_u32 s35, s17, s31
	s_add_u32 s34, s34, 0x100
	s_addc_u32 s35, s35, 0
	s_add_u32 s59, s27, s30
	s_addc_u32 s60, s55, s31
	s_cmpk_eq_i32 s30, 0xf00
	s_cselect_b32 s37, s21, s35
	s_cselect_b32 s36, s23, s34
	s_cselect_b32 s35, s56, s60
	s_cselect_b32 s34, s57, s59
	v_lshl_add_u64 v[168:169], v[140:141], 0, s[30:31]
	s_add_i32 m0, s40, 0xc000
	ds_read_b128 v[184:187], v146
	ds_read_b128 v[188:191], v146 offset:1024
	ds_read_b128 v[192:195], v146 offset:2048
	ds_read_b128 v[196:199], v146 offset:3072
	ds_read_b128 v[202:205], v146 offset:4096
	ds_read_b128 v[206:209], v146 offset:5120
	ds_read_b128 v[210:213], v146 offset:6144
	ds_read_b128 v[214:217], v146 offset:7168
	global_load_lds_dwordx4 v[168:169], off
	v_lshl_add_u64 v[168:169], v[142:143], 0, s[30:31]
	s_add_i32 m0, s40, 0xe000
	s_nop 0
	global_load_lds_dwordx4 v[168:169], off
	s_waitcnt vmcnt(8)
	global_load_dword v227, v226, s[44:45]
	v_add_u32_e32 v226, 0x10000, v226
	s_waitcnt lgkmcnt(0)
	s_barrier
	s_waitcnt lgkmcnt(0)
	v_mfma_f32_16x16x32_bf16 v[124:127], v[148:151], v[184:187], v[124:127]
	v_mfma_f32_16x16x32_bf16 v[120:123], v[156:159], v[184:187], v[120:123]
	v_mfma_f32_16x16x32_bf16 v[108:111], v[148:151], v[192:195], v[108:111]
	v_mfma_f32_16x16x32_bf16 v[104:107], v[156:159], v[192:195], v[104:107]
	v_mfma_f32_16x16x32_bf16 v[92:95], v[148:151], v[202:205], v[92:95]
	v_mfma_f32_16x16x32_bf16 v[88:91], v[156:159], v[202:205], v[88:91]
	v_mfma_f32_16x16x32_bf16 v[76:79], v[148:151], v[210:213], v[76:79]
	v_mfma_f32_16x16x32_bf16 v[72:75], v[156:159], v[210:213], v[72:75]
	v_mfma_f32_16x16x32_bf16 v[124:127], v[152:155], v[188:191], v[124:127]
	v_mfma_f32_16x16x32_bf16 v[120:123], v[160:163], v[188:191], v[120:123]
	v_mfma_f32_16x16x32_bf16 v[108:111], v[152:155], v[196:199], v[108:111]
	v_mfma_f32_16x16x32_bf16 v[104:107], v[160:163], v[196:199], v[104:107]
	v_mfma_f32_16x16x32_bf16 v[92:95], v[152:155], v[206:209], v[92:95]
	v_mfma_f32_16x16x32_bf16 v[88:91], v[160:163], v[206:209], v[88:91]
	v_mfma_f32_16x16x32_bf16 v[76:79], v[152:155], v[214:217], v[76:79]
	v_mfma_f32_16x16x32_bf16 v[72:75], v[160:163], v[214:217], v[72:75]
	v_mfma_f32_16x16x32_bf16 v[116:119], v[164:167], v[184:187], v[116:119]
	v_mfma_f32_16x16x32_bf16 v[112:115], v[176:179], v[184:187], v[112:115]
	v_mfma_f32_16x16x32_bf16 v[100:103], v[164:167], v[192:195], v[100:103]
	v_mfma_f32_16x16x32_bf16 v[96:99], v[176:179], v[192:195], v[96:99]
	v_mfma_f32_16x16x32_bf16 v[84:87], v[164:167], v[202:205], v[84:87]
	v_mfma_f32_16x16x32_bf16 v[80:83], v[176:179], v[202:205], v[80:83]
	v_mfma_f32_16x16x32_bf16 v[68:71], v[164:167], v[210:213], v[68:71]
	v_mfma_f32_16x16x32_bf16 v[64:67], v[176:179], v[210:213], v[64:67]
	v_mfma_f32_16x16x32_bf16 v[116:119], v[172:175], v[188:191], v[116:119]
	v_mfma_f32_16x16x32_bf16 v[112:115], v[180:183], v[188:191], v[112:115]
	v_mfma_f32_16x16x32_bf16 v[100:103], v[172:175], v[196:199], v[100:103]
	v_mfma_f32_16x16x32_bf16 v[96:99], v[180:183], v[196:199], v[96:99]
	v_mfma_f32_16x16x32_bf16 v[84:87], v[172:175], v[206:209], v[84:87]
	v_mfma_f32_16x16x32_bf16 v[80:83], v[180:183], v[206:209], v[80:83]
	v_mfma_f32_16x16x32_bf16 v[68:71], v[172:175], v[214:217], v[68:71]
	v_mfma_f32_16x16x32_bf16 v[64:67], v[180:183], v[214:217], v[64:67]
	s_barrier
	s_add_i32 s59, s53, s39
	v_lshl_add_u64 v[168:169], s[34:35], 0, v[128:129]
	s_mov_b32 m0, s59
	ds_read_b128 v[184:187], v146 offset:16384
	ds_read_b128 v[188:191], v146 offset:17408
	ds_read_b128 v[192:195], v146 offset:18432
	ds_read_b128 v[196:199], v146 offset:19456
	ds_read_b128 v[202:205], v146 offset:20480
	ds_read_b128 v[206:209], v146 offset:21504
	ds_read_b128 v[210:213], v146 offset:22528
	ds_read_b128 v[214:217], v146 offset:23552
	global_load_lds_dwordx4 v[168:169], off
	s_add_i32 m0, s59, 0x2000
	s_add_u32 s60, s34, 0x80000
	v_lshl_add_u64 v[218:219], s[34:35], 0, v[130:131]
	s_addc_u32 s61, s35, 0
	s_add_i32 s59, s54, s39
	global_load_lds_dwordx4 v[218:219], off
	v_lshl_add_u64 v[220:221], s[60:61], 0, v[128:129]
	s_mov_b32 m0, s59
	v_lshl_add_u64 v[222:223], s[36:37], 0, v[130:131]
	global_load_lds_dwordx4 v[220:221], off
	v_lshl_add_u64 v[220:221], s[60:61], 0, v[130:131]
	s_add_i32 m0, s59, 0x2000
	s_nop 0
	global_load_lds_dwordx4 v[220:221], off
	v_lshl_add_u64 v[220:221], s[36:37], 0, v[128:129]
	s_mov_b32 m0, s40
	s_nop 0
	global_load_lds_dwordx4 v[220:221], off
	s_mov_b32 m0, s41
	s_nop 0
	global_load_lds_dwordx4 v[222:223], off
	s_waitcnt vmcnt(9)
	s_waitcnt lgkmcnt(0)
	s_barrier
	s_waitcnt lgkmcnt(0)
	v_mfma_f32_16x16x32_bf16 v[60:63], v[148:151], v[184:187], v[60:63]
	v_mfma_f32_16x16x32_bf16 v[56:59], v[156:159], v[184:187], v[56:59]
	v_mfma_f32_16x16x32_bf16 v[44:47], v[148:151], v[192:195], v[44:47]
	v_mfma_f32_16x16x32_bf16 v[40:43], v[156:159], v[192:195], v[40:43]
	v_mfma_f32_16x16x32_bf16 v[28:31], v[148:151], v[202:205], v[28:31]
	v_mfma_f32_16x16x32_bf16 v[24:27], v[156:159], v[202:205], v[24:27]
	v_mfma_f32_16x16x32_bf16 v[12:15], v[148:151], v[210:213], v[12:15]
	v_mfma_f32_16x16x32_bf16 v[8:11], v[156:159], v[210:213], v[8:11]
	v_mfma_f32_16x16x32_bf16 v[60:63], v[152:155], v[188:191], v[60:63]
	v_mfma_f32_16x16x32_bf16 v[56:59], v[160:163], v[188:191], v[56:59]
	v_mfma_f32_16x16x32_bf16 v[44:47], v[152:155], v[196:199], v[44:47]
	v_mfma_f32_16x16x32_bf16 v[40:43], v[160:163], v[196:199], v[40:43]
	v_mfma_f32_16x16x32_bf16 v[28:31], v[152:155], v[206:209], v[28:31]
	v_mfma_f32_16x16x32_bf16 v[24:27], v[160:163], v[206:209], v[24:27]
	v_mfma_f32_16x16x32_bf16 v[12:15], v[152:155], v[214:217], v[12:15]
	v_mfma_f32_16x16x32_bf16 v[8:11], v[160:163], v[214:217], v[8:11]
	v_mfma_f32_16x16x32_bf16 v[52:55], v[164:167], v[184:187], v[52:55]
	v_mfma_f32_16x16x32_bf16 v[48:51], v[176:179], v[184:187], v[48:51]
	v_mfma_f32_16x16x32_bf16 v[36:39], v[164:167], v[192:195], v[36:39]
	v_mfma_f32_16x16x32_bf16 v[32:35], v[176:179], v[192:195], v[32:35]
	v_mfma_f32_16x16x32_bf16 v[20:23], v[164:167], v[202:205], v[20:23]
	v_mfma_f32_16x16x32_bf16 v[16:19], v[176:179], v[202:205], v[16:19]
	v_mfma_f32_16x16x32_bf16 v[4:7], v[164:167], v[210:213], v[4:7]
	v_mfma_f32_16x16x32_bf16 v[0:3], v[176:179], v[210:213], v[0:3]
	v_mfma_f32_16x16x32_bf16 v[52:55], v[172:175], v[188:191], v[52:55]
	v_mfma_f32_16x16x32_bf16 v[48:51], v[180:183], v[188:191], v[48:51]
	v_mfma_f32_16x16x32_bf16 v[36:39], v[172:175], v[196:199], v[36:39]
	v_mfma_f32_16x16x32_bf16 v[32:35], v[180:183], v[196:199], v[32:35]
	v_mfma_f32_16x16x32_bf16 v[20:23], v[172:175], v[206:209], v[20:23]
	v_mfma_f32_16x16x32_bf16 v[16:19], v[180:183], v[206:209], v[16:19]
	v_mfma_f32_16x16x32_bf16 v[4:7], v[172:175], v[214:217], v[4:7]
	v_mfma_f32_16x16x32_bf16 v[0:3], v[180:183], v[214:217], v[0:3]
	s_barrier
	s_add_i32 s59, 0, 0x18000
	v_add_u32_e32 v147, s59, v145
	s_add_i32 s60, 0, 0x1c000
	ds_read_b128 v[148:151], v147
	ds_read_b128 v[152:155], v147 offset:1024
	ds_read_b128 v[156:159], v147 offset:2048
	ds_read_b128 v[160:163], v147 offset:3072
	v_add_u32_e32 v147, s60, v145
	ds_read_b128 v[164:167], v147
	ds_read_b128 v[172:175], v147 offset:1024
	ds_read_b128 v[176:179], v147 offset:2048
	ds_read_b128 v[180:183], v147 offset:3072
	s_add_u32 s36, s36, 0x80000
	s_addc_u32 s37, s37, 0
	s_mov_b32 m0, s43
	v_lshl_add_u64 v[224:225], s[36:37], 0, v[128:129]
	ds_read_b128 v[184:187], v146 offset:32768
	ds_read_b128 v[188:191], v146 offset:33792
	ds_read_b128 v[192:195], v146 offset:34816
	ds_read_b128 v[196:199], v146 offset:35840
	ds_read_b128 v[202:205], v146 offset:36864
	ds_read_b128 v[206:209], v146 offset:37888
	ds_read_b128 v[210:213], v146 offset:38912
	ds_read_b128 v[214:217], v146 offset:39936
	global_load_lds_dwordx4 v[224:225], off
	v_lshl_add_u64 v[224:225], s[36:37], 0, v[130:131]
	s_mov_b32 m0, s48
	s_nop 0
	global_load_lds_dwordx4 v[224:225], off
	s_waitcnt vmcnt(9)
	s_waitcnt lgkmcnt(0)
	s_barrier
	s_waitcnt lgkmcnt(0)
	v_mfma_f32_16x16x32_bf16 v[124:127], v[148:151], v[184:187], v[124:127]
	v_mfma_f32_16x16x32_bf16 v[120:123], v[156:159], v[184:187], v[120:123]
	v_mfma_f32_16x16x32_bf16 v[108:111], v[148:151], v[192:195], v[108:111]
	v_mfma_f32_16x16x32_bf16 v[104:107], v[156:159], v[192:195], v[104:107]
	v_mfma_f32_16x16x32_bf16 v[92:95], v[148:151], v[202:205], v[92:95]
	v_mfma_f32_16x16x32_bf16 v[88:91], v[156:159], v[202:205], v[88:91]
	v_mfma_f32_16x16x32_bf16 v[76:79], v[148:151], v[210:213], v[76:79]
	v_mfma_f32_16x16x32_bf16 v[72:75], v[156:159], v[210:213], v[72:75]
	v_mfma_f32_16x16x32_bf16 v[124:127], v[152:155], v[188:191], v[124:127]
	v_mfma_f32_16x16x32_bf16 v[120:123], v[160:163], v[188:191], v[120:123]
	v_mfma_f32_16x16x32_bf16 v[108:111], v[152:155], v[196:199], v[108:111]
	v_mfma_f32_16x16x32_bf16 v[104:107], v[160:163], v[196:199], v[104:107]
	v_mfma_f32_16x16x32_bf16 v[92:95], v[152:155], v[206:209], v[92:95]
	v_mfma_f32_16x16x32_bf16 v[88:91], v[160:163], v[206:209], v[88:91]
	v_mfma_f32_16x16x32_bf16 v[76:79], v[152:155], v[214:217], v[76:79]
	v_mfma_f32_16x16x32_bf16 v[72:75], v[160:163], v[214:217], v[72:75]
	v_mfma_f32_16x16x32_bf16 v[116:119], v[164:167], v[184:187], v[116:119]
	v_mfma_f32_16x16x32_bf16 v[112:115], v[176:179], v[184:187], v[112:115]
	v_mfma_f32_16x16x32_bf16 v[100:103], v[164:167], v[192:195], v[100:103]
	v_mfma_f32_16x16x32_bf16 v[96:99], v[176:179], v[192:195], v[96:99]
	v_mfma_f32_16x16x32_bf16 v[84:87], v[164:167], v[202:205], v[84:87]
	v_mfma_f32_16x16x32_bf16 v[80:83], v[176:179], v[202:205], v[80:83]
	v_mfma_f32_16x16x32_bf16 v[68:71], v[164:167], v[210:213], v[68:71]
	v_mfma_f32_16x16x32_bf16 v[64:67], v[176:179], v[210:213], v[64:67]
	v_mfma_f32_16x16x32_bf16 v[116:119], v[172:175], v[188:191], v[116:119]
	v_mfma_f32_16x16x32_bf16 v[112:115], v[180:183], v[188:191], v[112:115]
	v_mfma_f32_16x16x32_bf16 v[100:103], v[172:175], v[196:199], v[100:103]
	v_mfma_f32_16x16x32_bf16 v[96:99], v[180:183], v[196:199], v[96:99]
	v_mfma_f32_16x16x32_bf16 v[84:87], v[172:175], v[206:209], v[84:87]
	v_mfma_f32_16x16x32_bf16 v[80:83], v[180:183], v[206:209], v[80:83]
	v_mfma_f32_16x16x32_bf16 v[68:71], v[172:175], v[214:217], v[68:71]
	v_mfma_f32_16x16x32_bf16 v[64:67], v[180:183], v[214:217], v[64:67]
	s_barrier
	s_add_i32 s36, s59, s39
	v_lshl_add_u64 v[168:169], v[168:169], 0, s[18:19]
	s_mov_b32 m0, s36
	ds_read_b128 v[184:187], v146 offset:49152
	ds_read_b128 v[188:191], v146 offset:50176
	ds_read_b128 v[192:195], v146 offset:51200
	ds_read_b128 v[196:199], v146 offset:52224
	ds_read_b128 v[202:205], v146 offset:53248
	ds_read_b128 v[206:209], v146 offset:54272
	ds_read_b128 v[210:213], v146 offset:55296
	ds_read_b128 v[214:217], v146 offset:56320
	global_load_lds_dwordx4 v[168:169], off
	s_add_i32 m0, s36, 0x2000
	s_add_u32 s34, s34, 0x80080
	v_lshl_add_u64 v[168:169], v[218:219], 0, s[18:19]
	s_addc_u32 s35, s35, 0
	s_add_i32 s36, s60, s39
	global_load_lds_dwordx4 v[168:169], off
	v_lshl_add_u64 v[168:169], s[34:35], 0, v[128:129]
	s_mov_b32 m0, s36
	s_nop 0
	global_load_lds_dwordx4 v[168:169], off
	v_lshl_add_u64 v[168:169], s[34:35], 0, v[130:131]
	s_add_i32 m0, s36, 0x2000
	s_nop 0
	global_load_lds_dwordx4 v[168:169], off
	v_lshl_add_u64 v[168:169], v[220:221], 0, s[18:19]
	s_mov_b32 m0, s49
	s_nop 0
	global_load_lds_dwordx4 v[168:169], off
	v_lshl_add_u64 v[168:169], v[222:223], 0, s[18:19]
	s_mov_b32 m0, s50
	s_nop 0
	global_load_lds_dwordx4 v[168:169], off
	s_waitcnt vmcnt(8)
	s_waitcnt lgkmcnt(0)
	s_barrier
	s_waitcnt lgkmcnt(0)
	v_mfma_f32_16x16x32_bf16 v[60:63], v[148:151], v[184:187], v[60:63]
	v_mfma_f32_16x16x32_bf16 v[56:59], v[156:159], v[184:187], v[56:59]
	v_mfma_f32_16x16x32_bf16 v[44:47], v[148:151], v[192:195], v[44:47]
	v_mfma_f32_16x16x32_bf16 v[40:43], v[156:159], v[192:195], v[40:43]
	v_mfma_f32_16x16x32_bf16 v[28:31], v[148:151], v[202:205], v[28:31]
	v_mfma_f32_16x16x32_bf16 v[24:27], v[156:159], v[202:205], v[24:27]
	v_mfma_f32_16x16x32_bf16 v[12:15], v[148:151], v[210:213], v[12:15]
	v_mfma_f32_16x16x32_bf16 v[8:11], v[156:159], v[210:213], v[8:11]
	v_mfma_f32_16x16x32_bf16 v[60:63], v[152:155], v[188:191], v[60:63]
	v_mfma_f32_16x16x32_bf16 v[56:59], v[160:163], v[188:191], v[56:59]
	v_mfma_f32_16x16x32_bf16 v[44:47], v[152:155], v[196:199], v[44:47]
	v_mfma_f32_16x16x32_bf16 v[40:43], v[160:163], v[196:199], v[40:43]
	v_mfma_f32_16x16x32_bf16 v[28:31], v[152:155], v[206:209], v[28:31]
	v_mfma_f32_16x16x32_bf16 v[24:27], v[160:163], v[206:209], v[24:27]
	v_mfma_f32_16x16x32_bf16 v[12:15], v[152:155], v[214:217], v[12:15]
	v_mfma_f32_16x16x32_bf16 v[8:11], v[160:163], v[214:217], v[8:11]
	v_mfma_f32_16x16x32_bf16 v[52:55], v[164:167], v[184:187], v[52:55]
	v_mfma_f32_16x16x32_bf16 v[48:51], v[176:179], v[184:187], v[48:51]
	v_mfma_f32_16x16x32_bf16 v[36:39], v[164:167], v[192:195], v[36:39]
	v_mfma_f32_16x16x32_bf16 v[32:35], v[176:179], v[192:195], v[32:35]
	v_mfma_f32_16x16x32_bf16 v[20:23], v[164:167], v[202:205], v[20:23]
	v_mfma_f32_16x16x32_bf16 v[16:19], v[176:179], v[202:205], v[16:19]
	v_mfma_f32_16x16x32_bf16 v[4:7], v[164:167], v[210:213], v[4:7]
	v_mfma_f32_16x16x32_bf16 v[0:3], v[176:179], v[210:213], v[0:3]
	v_mfma_f32_16x16x32_bf16 v[52:55], v[172:175], v[188:191], v[52:55]
	v_mfma_f32_16x16x32_bf16 v[48:51], v[180:183], v[188:191], v[48:51]
	v_mfma_f32_16x16x32_bf16 v[36:39], v[172:175], v[196:199], v[36:39]
	v_mfma_f32_16x16x32_bf16 v[32:35], v[180:183], v[196:199], v[32:35]
	v_mfma_f32_16x16x32_bf16 v[20:23], v[172:175], v[206:209], v[20:23]
	v_mfma_f32_16x16x32_bf16 v[16:19], v[180:183], v[206:209], v[16:19]
	v_mfma_f32_16x16x32_bf16 v[4:7], v[172:175], v[214:217], v[4:7]
	v_mfma_f32_16x16x32_bf16 v[0:3], v[180:183], v[214:217], v[0:3]
	s_barrier
	s_add_i32 s58, s58, 2
	s_add_u32 s30, s30, 0x100
	s_addc_u32 s31, s31, 0
	s_cmp_gt_u32 s58, 29
	s_cbranch_scc0 .LBB0_495
	s_setprio 0
	s_add_u32 s30, s27, 0xffffff00
	s_addc_u32 s31, s55, -1
	s_andn2_b64 vcc, exec, s[4:5]
	s_cbranch_vccnz .LBB0_498
	v_mov_b32_e32 v0, 0
	s_mov_b32 s51, s20
	s_mov_b32 s14, s22
	s_mov_b64 s[16:17], s[28:29]
	s_mov_b32 s52, s26
	v_mov_b32_e32 v1, v0
	v_mov_b32_e32 v2, v0
	v_mov_b32_e32 v3, v0
	v_mov_b32_e32 v4, v0
	v_mov_b32_e32 v5, v0
	v_mov_b32_e32 v6, v0
	v_mov_b32_e32 v7, v0
	v_mov_b32_e32 v16, v0
	v_mov_b32_e32 v17, v0
	v_mov_b32_e32 v18, v0
	v_mov_b32_e32 v19, v0
	v_mov_b32_e32 v20, v0
	v_mov_b32_e32 v21, v0
	v_mov_b32_e32 v22, v0
	v_mov_b32_e32 v23, v0
	v_mov_b32_e32 v32, v0
	v_mov_b32_e32 v33, v0
	v_mov_b32_e32 v34, v0
	v_mov_b32_e32 v35, v0
	v_mov_b32_e32 v36, v0
	v_mov_b32_e32 v37, v0
	v_mov_b32_e32 v38, v0
	v_mov_b32_e32 v39, v0
	v_mov_b32_e32 v48, v0
	v_mov_b32_e32 v49, v0
	v_mov_b32_e32 v50, v0
	v_mov_b32_e32 v51, v0
	v_mov_b32_e32 v52, v0
	v_mov_b32_e32 v53, v0
	v_mov_b32_e32 v54, v0
	v_mov_b32_e32 v55, v0
	v_mov_b32_e32 v8, v0
	v_mov_b32_e32 v9, v0
	v_mov_b32_e32 v10, v0
	v_mov_b32_e32 v11, v0
	v_mov_b32_e32 v12, v0
	v_mov_b32_e32 v13, v0
	v_mov_b32_e32 v14, v0
	v_mov_b32_e32 v15, v0
	v_mov_b32_e32 v24, v0
	v_mov_b32_e32 v25, v0
	v_mov_b32_e32 v26, v0
	v_mov_b32_e32 v27, v0
	v_mov_b32_e32 v28, v0
	v_mov_b32_e32 v29, v0
	v_mov_b32_e32 v30, v0
	v_mov_b32_e32 v31, v0
	v_mov_b32_e32 v40, v0
	v_mov_b32_e32 v41, v0
	v_mov_b32_e32 v42, v0
	v_mov_b32_e32 v43, v0
	v_mov_b32_e32 v44, v0
	v_mov_b32_e32 v45, v0
	v_mov_b32_e32 v46, v0
	v_mov_b32_e32 v47, v0
	v_mov_b32_e32 v56, v0
	v_mov_b32_e32 v57, v0
	v_mov_b32_e32 v58, v0
	v_mov_b32_e32 v59, v0
	v_mov_b32_e32 v60, v0
	v_mov_b32_e32 v61, v0
	v_mov_b32_e32 v62, v0
	v_mov_b32_e32 v63, v0
	v_mov_b32_e32 v64, v0
	v_mov_b32_e32 v65, v0
	v_mov_b32_e32 v66, v0
	v_mov_b32_e32 v67, v0
	v_mov_b32_e32 v68, v0
	v_mov_b32_e32 v69, v0
	v_mov_b32_e32 v70, v0
	v_mov_b32_e32 v71, v0
	v_mov_b32_e32 v80, v0
	v_mov_b32_e32 v81, v0
	v_mov_b32_e32 v82, v0
	v_mov_b32_e32 v83, v0
	v_mov_b32_e32 v84, v0
	v_mov_b32_e32 v85, v0
	v_mov_b32_e32 v86, v0
	v_mov_b32_e32 v87, v0
	v_mov_b32_e32 v96, v0
	v_mov_b32_e32 v97, v0
	v_mov_b32_e32 v98, v0
	v_mov_b32_e32 v99, v0
	v_mov_b32_e32 v100, v0
	v_mov_b32_e32 v101, v0
	v_mov_b32_e32 v102, v0
	v_mov_b32_e32 v103, v0
	v_mov_b32_e32 v112, v0
	v_mov_b32_e32 v113, v0
	v_mov_b32_e32 v114, v0
	v_mov_b32_e32 v115, v0
	v_mov_b32_e32 v116, v0
	v_mov_b32_e32 v117, v0
	v_mov_b32_e32 v118, v0
	v_mov_b32_e32 v119, v0
	v_mov_b32_e32 v72, v0
	v_mov_b32_e32 v73, v0
	v_mov_b32_e32 v74, v0
	v_mov_b32_e32 v75, v0
	v_mov_b32_e32 v76, v0
	v_mov_b32_e32 v77, v0
	v_mov_b32_e32 v78, v0
	v_mov_b32_e32 v79, v0
	v_mov_b32_e32 v88, v0
	v_mov_b32_e32 v89, v0
	v_mov_b32_e32 v90, v0
	v_mov_b32_e32 v91, v0
	v_mov_b32_e32 v92, v0
	v_mov_b32_e32 v93, v0
	v_mov_b32_e32 v94, v0
	v_mov_b32_e32 v95, v0
	v_mov_b32_e32 v104, v0
	v_mov_b32_e32 v105, v0
	v_mov_b32_e32 v106, v0
	v_mov_b32_e32 v107, v0
	v_mov_b32_e32 v108, v0
	v_mov_b32_e32 v109, v0
	v_mov_b32_e32 v110, v0
	v_mov_b32_e32 v111, v0
	v_mov_b32_e32 v120, v0
	v_mov_b32_e32 v121, v0
	v_mov_b32_e32 v122, v0
	v_mov_b32_e32 v123, v0
	v_mov_b32_e32 v124, v0
	v_mov_b32_e32 v125, v0
	v_mov_b32_e32 v126, v0
	v_mov_b32_e32 v127, v0
	s_andn2_b64 vcc, exec, s[0:1]
	s_cbranch_vccnz .LBB0_499
	s_branch .LBB0_500
